# sample pool unit: Wpool fragment loads with contiguous lane order + ds_bpermute to the MFMA layout (2 computing waves)
# baseline (speedup 1.0000x reference)
.LBB0_594:
	s_or_b64 exec, exec, s[48:49]
	s_mov_b32 s37, s73
	s_lshl_b64 s[24:25], s[36:37], 15
	s_add_u32 s24, s51, s24
	v_readlane_b32 s12, v253, 20
	v_bfe_u32 v225, v161, 4, 2
	s_addc_u32 s25, s12, s25
	v_lshlrev_b32_e32 v0, 8, v176
	v_lshl_add_u64 v[2:3], s[24:25], 0, v[0:1]
	v_lshlrev_b32_e32 v0, 4, v225
	v_lshl_add_u64 v[2:3], v[2:3], 0, v[0:1]
	v_lshlrev_b32_e32 v151, 4, v161
	v_and_b32_e32 v151, 0xf0, v151
	v_readfirstlane_b32 s12, v161
	s_cmpk_gt_i32 s12, 0x7f
	s_cbranch_scc1 .Lpw_skip
	v_and_b32_e32 v10, 63, v204
	v_lshrrev_b32_e32 v11, 2, v10
	v_and_b32_e32 v12, 15, v10
	v_sub_u32_e32 v11, v11, v12
	v_lshlrev_b32_e32 v11, 8, v11
	v_and_b32_e32 v12, 3, v10
	v_lshrrev_b32_e32 v13, 4, v10
	v_sub_u32_e32 v12, v12, v13
	v_lshl_add_u32 v10, v12, 4, v11
	v_ashrrev_i32_e32 v11, 31, v10
	v_lshl_add_u64 v[2:3], v[2:3], 0, v[10:11]
	s_movk_i32 s12, 0x1000
	v_add_co_u32_e32 v4, vcc, s12, v2
	s_movk_i32 s12, 0x2000
	s_nop 0
	v_addc_co_u32_e32 v5, vcc, 0, v3, vcc
	v_add_co_u32_e32 v126, vcc, s12, v2
	s_movk_i32 s12, 0x3000
	s_nop 0
	v_addc_co_u32_e32 v127, vcc, 0, v3, vcc
	v_add_co_u32_e32 v6, vcc, s12, v2
	s_movk_i32 s12, 0x4000
	s_nop 0
	v_addc_co_u32_e32 v7, vcc, 0, v3, vcc
	v_add_co_u32_e32 v8, vcc, s12, v2
	s_movk_i32 s12, 0x5000
	s_nop 0
	v_addc_co_u32_e32 v9, vcc, 0, v3, vcc
	global_load_dwordx4 v[98:101], v[2:3], off
	global_load_dwordx4 v[78:81], v[2:3], off offset:64
	global_load_dwordx4 v[66:69], v[2:3], off offset:128
	global_load_dwordx4 v[34:37], v[2:3], off offset:192
	global_load_dwordx4 v[70:73], v[4:5], off offset:64
	global_load_dwordx4 v[74:77], v[4:5], off offset:128
	global_load_dwordx4 v[38:41], v[126:127], off
	global_load_dwordx4 v[42:45], v[126:127], off offset:64
	global_load_dwordx4 v[46:49], v[126:127], off offset:128
	global_load_dwordx4 v[50:53], v[126:127], off offset:192
	global_load_dwordx4 v[122:125], v[4:5], off offset:192
	global_load_dwordx4 v[82:85], v[6:7], off offset:64
	global_load_dwordx4 v[86:89], v[6:7], off offset:128
	global_load_dwordx4 v[90:93], v[6:7], off offset:192
	global_load_dwordx4 v[102:105], v[8:9], off offset:-4096
	global_load_dwordx4 v[54:57], v[8:9], off
	global_load_dwordx4 v[58:61], v[8:9], off offset:64
	global_load_dwordx4 v[62:65], v[8:9], off offset:128
	v_add_co_u32_e32 v4, vcc, s12, v2
	s_movk_i32 s12, 0x6000
	s_nop 0
	v_addc_co_u32_e32 v5, vcc, 0, v3, vcc
	v_add_co_u32_e32 v6, vcc, s12, v2
	s_nop 0
	v_addc_co_u32_e32 v7, vcc, 0, v3, vcc
	global_load_dwordx4 v[118:121], v[8:9], off offset:192
	global_load_dwordx4 v[110:113], v[6:7], off offset:-4096
	global_load_dwordx4 v[106:109], v[4:5], off offset:64
	global_load_dwordx4 v[94:97], v[4:5], off offset:128
	global_load_dwordx4 v[30:33], v[6:7], off
	global_load_dwordx4 v[26:29], v[6:7], off offset:64
	global_load_dwordx4 v[22:25], v[6:7], off offset:128
	global_load_dwordx4 v[18:21], v[6:7], off offset:192
	v_add_co_u32_e32 v2, vcc, 0x7000, v2
	s_nop 0
	v_addc_co_u32_e32 v3, vcc, 0, v3, vcc
	global_load_dwordx4 v[114:117], v[4:5], off offset:192
	global_load_dwordx4 v[14:17], v[2:3], off
	global_load_dwordx4 v[10:13], v[2:3], off offset:64
	global_load_dwordx4 v[6:9], v[2:3], off offset:128
	s_nop 0
	global_load_dwordx4 v[126:129], v[126:127], off offset:-4096
	s_nop 0
	global_load_dwordx4 v[2:5], v[2:3], off offset:192

.LBB0_621:
	v_and_b32_e32 v212, 63, v204
	v_lshrrev_b32_e32 v213, 4, v212
	v_and_b32_e32 v212, 15, v212
	v_lshlrev_b32_e32 v213, 2, v213
	v_lshl_or_b32 v212, v212, 4, v213
	ds_bpermute_b32 v2, v212, v2
	ds_bpermute_b32 v3, v212, v3
	ds_bpermute_b32 v4, v212, v4
	ds_bpermute_b32 v5, v212, v5
	ds_bpermute_b32 v6, v212, v6
	ds_bpermute_b32 v7, v212, v7
	ds_bpermute_b32 v8, v212, v8
	ds_bpermute_b32 v9, v212, v9
	ds_bpermute_b32 v10, v212, v10
	ds_bpermute_b32 v11, v212, v11
	ds_bpermute_b32 v12, v212, v12
	ds_bpermute_b32 v13, v212, v13
	ds_bpermute_b32 v14, v212, v14
	ds_bpermute_b32 v15, v212, v15
	ds_bpermute_b32 v16, v212, v16
	ds_bpermute_b32 v17, v212, v17
	s_waitcnt lgkmcnt(0)
	ds_bpermute_b32 v18, v212, v18
	ds_bpermute_b32 v19, v212, v19
	ds_bpermute_b32 v20, v212, v20
	ds_bpermute_b32 v21, v212, v21
	ds_bpermute_b32 v22, v212, v22
	ds_bpermute_b32 v23, v212, v23
	ds_bpermute_b32 v24, v212, v24
	ds_bpermute_b32 v25, v212, v25
	ds_bpermute_b32 v26, v212, v26
	ds_bpermute_b32 v27, v212, v27
	ds_bpermute_b32 v28, v212, v28
	ds_bpermute_b32 v29, v212, v29
	ds_bpermute_b32 v30, v212, v30
	ds_bpermute_b32 v31, v212, v31
	ds_bpermute_b32 v32, v212, v32
	ds_bpermute_b32 v33, v212, v33
	s_waitcnt lgkmcnt(0)
	ds_bpermute_b32 v34, v212, v34
	ds_bpermute_b32 v35, v212, v35
	ds_bpermute_b32 v36, v212, v36
	ds_bpermute_b32 v37, v212, v37
	ds_bpermute_b32 v38, v212, v38
	ds_bpermute_b32 v39, v212, v39
	ds_bpermute_b32 v40, v212, v40
	ds_bpermute_b32 v41, v212, v41
	ds_bpermute_b32 v42, v212, v42
	ds_bpermute_b32 v43, v212, v43
	ds_bpermute_b32 v44, v212, v44
	ds_bpermute_b32 v45, v212, v45
	ds_bpermute_b32 v46, v212, v46
	ds_bpermute_b32 v47, v212, v47
	ds_bpermute_b32 v48, v212, v48
	ds_bpermute_b32 v49, v212, v49
	s_waitcnt lgkmcnt(0)
	ds_bpermute_b32 v50, v212, v50
	ds_bpermute_b32 v51, v212, v51
	ds_bpermute_b32 v52, v212, v52
	ds_bpermute_b32 v53, v212, v53
	ds_bpermute_b32 v54, v212, v54
	ds_bpermute_b32 v55, v212, v55
	ds_bpermute_b32 v56, v212, v56
	ds_bpermute_b32 v57, v212, v57
	ds_bpermute_b32 v58, v212, v58
	ds_bpermute_b32 v59, v212, v59
	ds_bpermute_b32 v60, v212, v60
	ds_bpermute_b32 v61, v212, v61
	ds_bpermute_b32 v62, v212, v62
	ds_bpermute_b32 v63, v212, v63
	ds_bpermute_b32 v64, v212, v64
	ds_bpermute_b32 v65, v212, v65
	s_waitcnt lgkmcnt(0)
	ds_bpermute_b32 v66, v212, v66
	ds_bpermute_b32 v67, v212, v67
	ds_bpermute_b32 v68, v212, v68
	ds_bpermute_b32 v69, v212, v69
	ds_bpermute_b32 v70, v212, v70
	ds_bpermute_b32 v71, v212, v71
	ds_bpermute_b32 v72, v212, v72
	ds_bpermute_b32 v73, v212, v73
	ds_bpermute_b32 v74, v212, v74
	ds_bpermute_b32 v75, v212, v75
	ds_bpermute_b32 v76, v212, v76
	ds_bpermute_b32 v77, v212, v77
	ds_bpermute_b32 v78, v212, v78
	ds_bpermute_b32 v79, v212, v79
	ds_bpermute_b32 v80, v212, v80
	ds_bpermute_b32 v81, v212, v81
	s_waitcnt lgkmcnt(0)
	ds_bpermute_b32 v82, v212, v82
	ds_bpermute_b32 v83, v212, v83
	ds_bpermute_b32 v84, v212, v84
	ds_bpermute_b32 v85, v212, v85
	ds_bpermute_b32 v86, v212, v86
	ds_bpermute_b32 v87, v212, v87
	ds_bpermute_b32 v88, v212, v88
	ds_bpermute_b32 v89, v212, v89
	ds_bpermute_b32 v90, v212, v90
	ds_bpermute_b32 v91, v212, v91
	ds_bpermute_b32 v92, v212, v92
	ds_bpermute_b32 v93, v212, v93
	ds_bpermute_b32 v94, v212, v94
	ds_bpermute_b32 v95, v212, v95
	ds_bpermute_b32 v96, v212, v96
	ds_bpermute_b32 v97, v212, v97
	s_waitcnt lgkmcnt(0)
	ds_bpermute_b32 v98, v212, v98
	ds_bpermute_b32 v99, v212, v99
	ds_bpermute_b32 v100, v212, v100
	ds_bpermute_b32 v101, v212, v101
	ds_bpermute_b32 v102, v212, v102
	ds_bpermute_b32 v103, v212, v103
	ds_bpermute_b32 v104, v212, v104
	ds_bpermute_b32 v105, v212, v105
	ds_bpermute_b32 v106, v212, v106
	ds_bpermute_b32 v107, v212, v107
	ds_bpermute_b32 v108, v212, v108
	ds_bpermute_b32 v109, v212, v109
	ds_bpermute_b32 v110, v212, v110
	ds_bpermute_b32 v111, v212, v111
	ds_bpermute_b32 v112, v212, v112
	ds_bpermute_b32 v113, v212, v113
	s_waitcnt lgkmcnt(0)
	ds_bpermute_b32 v114, v212, v114
	ds_bpermute_b32 v115, v212, v115
	ds_bpermute_b32 v116, v212, v116
	ds_bpermute_b32 v117, v212, v117
	ds_bpermute_b32 v118, v212, v118
	ds_bpermute_b32 v119, v212, v119
	ds_bpermute_b32 v120, v212, v120
	ds_bpermute_b32 v121, v212, v121
	ds_bpermute_b32 v122, v212, v122
	ds_bpermute_b32 v123, v212, v123
	ds_bpermute_b32 v124, v212, v124
	ds_bpermute_b32 v125, v212, v125
	ds_bpermute_b32 v126, v212, v126
	ds_bpermute_b32 v127, v212, v127
	ds_bpermute_b32 v128, v212, v128
	ds_bpermute_b32 v129, v212, v129
	s_waitcnt lgkmcnt(0)
	v_cvt_f32_i32_e32 v0, s23
	s_addk_i32 s22, 0x4000
	s_lshl_b32 s72, s72, 1
	v_div_scale_f32 v212, s[0:1], v0, v0, 1.0
	v_rcp_f32_e32 v213, v212
	v_div_scale_f32 v214, vcc, 1.0, v0, 1.0
	v_fma_f32 v215, -v212, v213, 1.0
	v_fmac_f32_e32 v213, v215, v213
	v_mul_f32_e32 v215, v214, v213
	v_fma_f32 v222, -v212, v215, v214
	v_fmac_f32_e32 v215, v222, v213
	v_fma_f32 v212, -v212, v215, v214
	v_div_fmas_f32 v212, v212, v213, v215
	v_div_fixup_f32 v0, v212, v0, 1.0
	v_pk_fma_f32 v[138:139], v[0:1], v[144:145], v[138:139] op_sel_hi:[0,1,1] neg_lo:[0,0,1] neg_hi:[0,0,1]
	v_pk_fma_f32 v[136:137], v[0:1], v[142:143], v[136:137] op_sel_hi:[0,1,1] neg_lo:[0,0,1] neg_hi:[0,0,1]
	v_pk_fma_f32 v[134:135], v[0:1], v[140:141], v[134:135] op_sel_hi:[0,1,1] neg_lo:[0,0,1] neg_hi:[0,0,1]
	v_pk_fma_f32 v[130:131], v[0:1], v[132:133], v[130:131] op_sel_hi:[0,1,1] neg_lo:[0,0,1] neg_hi:[0,0,1]
	v_cvt_pk_bf16_f32 v138, v138, v139
	v_cvt_pk_bf16_f32 v139, v136, v137
	v_cvt_pk_bf16_f32 v140, v134, v135
	v_cvt_pk_bf16_f32 v141, v130, v131
	v_pk_fma_f32 v[154:155], v[0:1], v[160:161], v[154:155] op_sel_hi:[0,1,1] neg_lo:[0,0,1] neg_hi:[0,0,1]
	v_pk_fma_f32 v[152:153], v[0:1], v[158:159], v[152:153] op_sel_hi:[0,1,1] neg_lo:[0,0,1] neg_hi:[0,0,1]
	v_mfma_f32_16x16x32_bf16 v[98:101], v[98:101], v[138:141], 0
	v_fma_f32 v150, v0, v156, -v150
	v_fma_f32 v151, v0, v157, -v151
	v_pk_fma_f32 v[146:147], v[0:1], v[146:147], v[148:149] op_sel_hi:[0,1,1] neg_lo:[0,0,1] neg_hi:[0,0,1]
	v_cvt_pk_bf16_f32 v154, v154, v155
	v_mfma_f32_16x16x32_bf16 v[38:41], v[38:41], v[138:141], 0
	v_cvt_pk_bf16_f32 v155, v152, v153
	v_cvt_pk_bf16_f32 v156, v150, v151
	v_cvt_pk_bf16_f32 v157, v146, v147
	v_pk_fma_f32 v[170:171], v[0:1], v[186:187], v[170:171] op_sel_hi:[0,1,1] neg_lo:[0,0,1] neg_hi:[0,0,1]
	v_pk_fma_f32 v[174:175], v[0:1], v[174:175], v[168:169] op_sel_hi:[0,1,1] neg_lo:[0,0,1] neg_hi:[0,0,1]
	v_mfma_f32_16x16x32_bf16 v[78:81], v[78:81], v[154:157], v[98:101]
	v_fma_f32 v166, v0, v172, -v166
	v_fma_f32 v167, v0, v173, -v167
	v_pk_fma_f32 v[162:163], v[0:1], v[162:163], v[164:165] op_sel_hi:[0,1,1] neg_lo:[0,0,1] neg_hi:[0,0,1]
	v_cvt_pk_bf16_f32 v168, v170, v171
	v_mfma_f32_16x16x32_bf16 v[38:41], v[42:45], v[154:157], v[38:41]
	v_cvt_pk_bf16_f32 v169, v174, v175
	v_cvt_pk_bf16_f32 v170, v166, v167
	v_cvt_pk_bf16_f32 v171, v162, v163
	v_pk_fma_f32 v[130:131], v[0:1], v[202:203], v[188:189] op_sel_hi:[0,1,1] neg_lo:[0,0,1] neg_hi:[0,0,1]
	v_pk_fma_f32 v[98:99], v[0:1], v[200:201], v[192:193] op_sel_hi:[0,1,1] neg_lo:[0,0,1] neg_hi:[0,0,1]
	v_mfma_f32_16x16x32_bf16 v[66:69], v[66:69], v[168:171], v[78:81]
	v_cvt_pk_bf16_f32 v130, v130, v131
	v_cvt_pk_bf16_f32 v131, v98, v99
	v_pk_fma_f32 v[98:99], v[0:1], v[198:199], v[194:195] op_sel_hi:[0,1,1] neg_lo:[0,0,1] neg_hi:[0,0,1]
	v_mfma_f32_16x16x32_bf16 v[38:41], v[46:49], v[168:171], v[38:41]
	v_fma_f32 v78, v0, v190, -v196
	v_fma_f32 v79, v0, v191, -v197
	v_cvt_pk_bf16_f32 v132, v98, v99
	v_cvt_pk_bf16_f32 v133, v78, v79
	v_mfma_f32_16x16x32_bf16 v[42:45], v[102:105], v[138:141], 0
	v_or_b32_e32 v0, s22, v176
	v_mfma_f32_16x16x32_bf16 v[34:37], v[34:37], v[130:133], v[66:69]
	v_mfma_f32_16x16x32_bf16 v[66:69], v[126:129], v[138:141], 0
	v_mfma_f32_16x16x32_bf16 v[38:41], v[50:53], v[130:133], v[38:41]
	s_nop 5
	v_cvt_pk_bf16_f32 v34, v34, v35
	v_cvt_pk_bf16_f32 v35, v36, v37
	v_mfma_f32_16x16x32_bf16 v[46:49], v[54:57], v[138:141], 0
	v_add_u32_e32 v54, s19, v0
	v_ashrrev_i32_e32 v55, 31, v54
	v_lshlrev_b64 v[54:55], 11, v[54:55]
	v_mfma_f32_16x16x32_bf16 v[50:53], v[110:113], v[138:141], 0
	v_lshl_add_u64 v[54:55], s[76:77], 0, v[54:55]
	v_lshl_add_u64 v[54:55], v[54:55], 0, s[72:73]
	v_lshlrev_b32_e32 v0, 3, v225
	v_mfma_f32_16x16x32_bf16 v[30:33], v[30:33], v[138:141], 0
	v_lshl_add_u64 v[54:55], v[54:55], 0, v[0:1]
	global_store_dwordx2 v[54:55], v[34:35], off
	v_mfma_f32_16x16x32_bf16 v[14:17], v[14:17], v[138:141], 0
	v_mfma_f32_16x16x32_bf16 v[42:45], v[82:85], v[154:157], v[42:45]
	v_mfma_f32_16x16x32_bf16 v[66:69], v[70:73], v[154:157], v[66:69]
	v_mfma_f32_16x16x32_bf16 v[46:49], v[58:61], v[154:157], v[46:49]
	v_mfma_f32_16x16x32_bf16 v[50:53], v[106:109], v[154:157], v[50:53]
	v_mfma_f32_16x16x32_bf16 v[26:29], v[26:29], v[154:157], v[30:33]
	v_mfma_f32_16x16x32_bf16 v[10:13], v[10:13], v[154:157], v[14:17]
	v_mfma_f32_16x16x32_bf16 v[42:45], v[86:89], v[168:171], v[42:45]
	v_mfma_f32_16x16x32_bf16 v[66:69], v[74:77], v[168:171], v[66:69]
	v_mfma_f32_16x16x32_bf16 v[46:49], v[62:65], v[168:171], v[46:49]
	v_mfma_f32_16x16x32_bf16 v[50:53], v[94:97], v[168:171], v[50:53]
	v_mfma_f32_16x16x32_bf16 v[22:25], v[22:25], v[168:171], v[26:29]
	v_mfma_f32_16x16x32_bf16 v[6:9], v[6:9], v[168:171], v[10:13]
	s_nop 1
	v_cvt_pk_bf16_f32 v26, v38, v39
	v_cvt_pk_bf16_f32 v27, v40, v41
	global_store_dwordx2 v[54:55], v[26:27], off offset:64
	v_mfma_f32_16x16x32_bf16 v[42:45], v[90:93], v[130:133], v[42:45]
	v_mfma_f32_16x16x32_bf16 v[66:69], v[122:125], v[130:133], v[66:69]
	v_mfma_f32_16x16x32_bf16 v[46:49], v[118:121], v[130:133], v[46:49]
	v_mfma_f32_16x16x32_bf16 v[50:53], v[114:117], v[130:133], v[50:53]
	s_nop 5
	v_cvt_pk_bf16_f32 v30, v66, v67
	v_cvt_pk_bf16_f32 v31, v68, v69
	global_store_dwordx2 v[54:55], v[30:31], off offset:32
	v_mfma_f32_16x16x32_bf16 v[18:21], v[18:21], v[130:133], v[22:25]
	v_mfma_f32_16x16x32_bf16 v[2:5], v[2:5], v[130:133], v[6:9]
	s_nop 1
	v_cvt_pk_bf16_f32 v22, v42, v43
	v_cvt_pk_bf16_f32 v23, v44, v45
	global_store_dwordx2 v[54:55], v[22:23], off offset:96
	v_cvt_pk_bf16_f32 v22, v46, v47
	v_cvt_pk_bf16_f32 v23, v48, v49
	v_cvt_pk_bf16_f32 v14, v50, v51
	v_cvt_pk_bf16_f32 v15, v52, v53
	v_cvt_pk_bf16_f32 v10, v18, v19
	v_cvt_pk_bf16_f32 v11, v20, v21
	v_cvt_pk_bf16_f32 v2, v2, v3
	v_cvt_pk_bf16_f32 v3, v4, v5
	global_store_dwordx2 v[54:55], v[22:23], off offset:128
	global_store_dwordx2 v[54:55], v[14:15], off offset:160
	global_store_dwordx2 v[54:55], v[10:11], off offset:192
	global_store_dwordx2 v[54:55], v[2:3], off offset:224
